# grid barrier: non-leader workgroups spin on the cross-XCD generation word directly instead of the per-XCD relay word (one hop less per grid barrier)
# baseline (speedup 1.0000x reference)
.LBB0_112:
	s_or_b64 exec, exec, s[12:13]
	v_cvt_f32_u32_e32 v4, v2
	s_waitcnt vmcnt(0)
	v_readfirstlane_b32 s2, v3
	v_sub_u32_e32 v3, 0, v2
	v_rcp_iflag_f32_e32 v4, v4
	v_add_u32_e32 v5, s2, v1
	v_mul_f32_e32 v4, 0x4f7ffffe, v4
	v_cvt_u32_f32_e32 v4, v4
	v_mul_lo_u32 v1, v3, v4
	v_mul_hi_u32 v1, v4, v1
	v_add_u32_e32 v1, v4, v1
	v_mul_hi_u32 v1, v5, v1
	v_mul_lo_u32 v3, v1, v2
	v_sub_u32_e32 v3, v5, v3
	v_add_u32_e32 v4, 1, v1
	v_cmp_ge_u32_e32 vcc, v3, v2
	s_nop 1
	v_cndmask_b32_e32 v1, v1, v4, vcc
	v_sub_u32_e32 v4, v3, v2
	v_cndmask_b32_e32 v3, v3, v4, vcc
	v_add_u32_e32 v4, 1, v1
	v_cmp_ge_u32_e32 vcc, v3, v2
	v_add_u32_e32 v3, 1, v5
	s_nop 0
	v_cndmask_b32_e32 v1, v1, v4, vcc
	v_mul_lo_u32 v4, v2, v1
	v_add_u32_e32 v2, v4, v2
	v_cmp_ne_u32_e32 vcc, v3, v2
	s_and_saveexec_b64 s[2:3], vcc
	s_xor_b64 s[10:11], exec, s[2:3]
	s_cbranch_execz .LBB0_126
	s_movk_i32 s2, 0xd40
	s_mov_b32 s3, 0
	s_lshl_b64 s[2:3], s[2:3], 2
	s_add_u32 s14, s6, s2
	s_addc_u32 s15, s7, s3
	s_waitcnt lgkmcnt(0)
	v_mov_b32_e32 v0, 0
	global_load_dword v2, v0, s[14:15] sc1
	s_waitcnt vmcnt(0)
	v_cmp_eq_u32_e32 vcc, v2, v1
	s_and_saveexec_b64 s[12:13], vcc
	s_cbranch_execz .LBB0_125
	s_mov_b32 s2, 1
	s_mov_b64 s[16:17], 0
	s_branch .LBB0_116

.LBB0_180:
	s_or_b64 exec, exec, s[10:11]
	v_cvt_f32_u32_e32 v4, v2
	s_waitcnt vmcnt(0)
	v_readfirstlane_b32 s1, v3
	v_sub_u32_e32 v3, 0, v2
	v_rcp_iflag_f32_e32 v4, v4
	v_add_u32_e32 v5, s1, v1
	v_mul_f32_e32 v4, 0x4f7ffffe, v4
	v_cvt_u32_f32_e32 v4, v4
	v_mul_lo_u32 v1, v3, v4
	v_mul_hi_u32 v1, v4, v1
	v_add_u32_e32 v1, v4, v1
	v_mul_hi_u32 v1, v5, v1
	v_mul_lo_u32 v3, v1, v2
	v_sub_u32_e32 v3, v5, v3
	v_add_u32_e32 v4, 1, v1
	v_cmp_ge_u32_e32 vcc, v3, v2
	s_nop 1
	v_cndmask_b32_e32 v1, v1, v4, vcc
	v_sub_u32_e32 v4, v3, v2
	v_cndmask_b32_e32 v3, v3, v4, vcc
	v_add_u32_e32 v4, 1, v1
	v_cmp_ge_u32_e32 vcc, v3, v2
	v_add_u32_e32 v3, 1, v5
	s_nop 0
	v_cndmask_b32_e32 v1, v1, v4, vcc
	v_mul_lo_u32 v4, v2, v1
	v_add_u32_e32 v2, v4, v2
	v_cmp_ne_u32_e32 vcc, v3, v2
	s_and_saveexec_b64 s[2:3], vcc
	s_xor_b64 s[8:9], exec, s[2:3]
	s_cbranch_execz .LBB0_194
	s_movk_i32 s2, 0xd40
	s_mov_b32 s3, 0
	s_lshl_b64 s[2:3], s[2:3], 2
	s_add_u32 s12, s4, s2
	s_addc_u32 s13, s5, s3
	s_waitcnt lgkmcnt(0)
	v_mov_b32_e32 v0, 0
	global_load_dword v2, v0, s[12:13] sc1
	s_waitcnt vmcnt(0)
	v_cmp_eq_u32_e32 vcc, v2, v1
	s_and_saveexec_b64 s[10:11], vcc
	s_cbranch_execz .LBB0_193
	s_mov_b32 s1, 1
	s_mov_b64 s[14:15], 0
	s_branch .LBB0_184

.LBB0_379:
	s_or_b64 exec, exec, s[46:47]
	v_cvt_f32_u32_e32 v5, v3
	s_waitcnt vmcnt(0)
	v_readfirstlane_b32 s2, v4
	v_sub_u32_e32 v4, 0, v3
	v_rcp_iflag_f32_e32 v5, v5
	v_add_u32_e32 v6, s2, v2
	v_mul_f32_e32 v5, 0x4f7ffffe, v5
	v_cvt_u32_f32_e32 v5, v5
	v_mul_lo_u32 v2, v4, v5
	v_mul_hi_u32 v2, v5, v2
	v_add_u32_e32 v2, v5, v2
	v_mul_hi_u32 v2, v6, v2
	v_mul_lo_u32 v4, v2, v3
	v_sub_u32_e32 v4, v6, v4
	v_add_u32_e32 v5, 1, v2
	v_cmp_ge_u32_e32 vcc, v4, v3
	s_nop 1
	v_cndmask_b32_e32 v2, v2, v5, vcc
	v_sub_u32_e32 v5, v4, v3
	v_cndmask_b32_e32 v4, v4, v5, vcc
	v_add_u32_e32 v5, 1, v2
	v_cmp_ge_u32_e32 vcc, v4, v3
	v_add_u32_e32 v4, 1, v6
	s_nop 0
	v_cndmask_b32_e32 v2, v2, v5, vcc
	v_mul_lo_u32 v5, v3, v2
	v_add_u32_e32 v3, v5, v3
	v_cmp_ne_u32_e32 vcc, v4, v3
	s_and_saveexec_b64 s[2:3], vcc
	s_xor_b64 s[8:9], exec, s[2:3]
	s_cbranch_execz .LBB0_393
	s_movk_i32 s14, 0xd40
	s_lshl_b64 s[2:3], s[14:15], 2
	s_add_u32 s48, s4, s2
	s_addc_u32 s49, s5, s3
	s_waitcnt lgkmcnt(0)
	global_load_dword v0, v1, s[48:49] sc1
	s_waitcnt vmcnt(0)
	v_cmp_eq_u32_e32 vcc, v0, v2
	s_and_saveexec_b64 s[46:47], vcc
	s_cbranch_execz .LBB0_392
	s_mov_b32 s2, 1
	s_mov_b64 s[50:51], 0
	s_branch .LBB0_383

.LBB0_1194:
	s_or_b64 exec, exec, s[46:47]
	v_cvt_f32_u32_e32 v5, v3
	s_waitcnt vmcnt(0)
	v_readfirstlane_b32 s1, v4
	v_sub_u32_e32 v4, 0, v3
	v_rcp_iflag_f32_e32 v5, v5
	v_add_u32_e32 v6, s1, v2
	v_mul_f32_e32 v5, 0x4f7ffffe, v5
	v_cvt_u32_f32_e32 v5, v5
	v_mul_lo_u32 v2, v4, v5
	v_mul_hi_u32 v2, v5, v2
	v_add_u32_e32 v2, v5, v2
	v_mul_hi_u32 v2, v6, v2
	v_mul_lo_u32 v4, v2, v3
	v_sub_u32_e32 v4, v6, v4
	v_add_u32_e32 v5, 1, v2
	v_cmp_ge_u32_e32 vcc, v4, v3
	s_nop 1
	v_cndmask_b32_e32 v2, v2, v5, vcc
	v_sub_u32_e32 v5, v4, v3
	v_cndmask_b32_e32 v4, v4, v5, vcc
	v_add_u32_e32 v5, 1, v2
	v_cmp_ge_u32_e32 vcc, v4, v3
	v_add_u32_e32 v4, 1, v6
	s_nop 0
	v_cndmask_b32_e32 v2, v2, v5, vcc
	v_mul_lo_u32 v5, v3, v2
	v_add_u32_e32 v3, v5, v3
	v_cmp_ne_u32_e32 vcc, v4, v3
	s_and_saveexec_b64 s[2:3], vcc
	s_xor_b64 s[8:9], exec, s[2:3]
	s_cbranch_execz .LBB0_1208
	s_movk_i32 s14, 0xd40
	s_lshl_b64 s[2:3], s[14:15], 2
	s_add_u32 s48, s4, s2
	s_addc_u32 s49, s5, s3
	s_waitcnt lgkmcnt(0)
	global_load_dword v0, v1, s[48:49] sc1
	s_waitcnt vmcnt(0)
	v_cmp_eq_u32_e32 vcc, v0, v2
	s_and_saveexec_b64 s[46:47], vcc
	s_cbranch_execz .LBB0_1207
	s_mov_b32 s1, 1
	s_mov_b64 s[50:51], 0
	s_branch .LBB0_1198

.LBB0_1476:
	s_or_b64 exec, exec, s[10:11]
	v_cvt_f32_u32_e32 v5, v3
	s_waitcnt vmcnt(0)
	v_readfirstlane_b32 s2, v4
	v_sub_u32_e32 v4, 0, v3
	v_rcp_iflag_f32_e32 v5, v5
	v_add_u32_e32 v6, s2, v2
	v_mul_f32_e32 v5, 0x4f7ffffe, v5
	v_cvt_u32_f32_e32 v5, v5
	v_mul_lo_u32 v2, v4, v5
	v_mul_hi_u32 v2, v5, v2
	v_add_u32_e32 v2, v5, v2
	v_mul_hi_u32 v2, v6, v2
	v_mul_lo_u32 v4, v2, v3
	v_sub_u32_e32 v4, v6, v4
	v_add_u32_e32 v5, 1, v2
	v_cmp_ge_u32_e32 vcc, v4, v3
	s_nop 1
	v_cndmask_b32_e32 v2, v2, v5, vcc
	v_sub_u32_e32 v5, v4, v3
	v_cndmask_b32_e32 v4, v4, v5, vcc
	v_add_u32_e32 v5, 1, v2
	v_cmp_ge_u32_e32 vcc, v4, v3
	v_add_u32_e32 v4, 1, v6
	s_nop 0
	v_cndmask_b32_e32 v2, v2, v5, vcc
	v_mul_lo_u32 v5, v3, v2
	v_add_u32_e32 v3, v5, v3
	v_cmp_ne_u32_e32 vcc, v4, v3
	s_and_saveexec_b64 s[2:3], vcc
	s_xor_b64 s[8:9], exec, s[2:3]
	s_cbranch_execz .LBB0_1490
	s_movk_i32 s14, 0xd40
	s_lshl_b64 s[2:3], s[14:15], 2
	s_add_u32 s12, s4, s2
	s_addc_u32 s13, s5, s3
	s_waitcnt lgkmcnt(0)
	global_load_dword v0, v1, s[12:13] sc1
	s_waitcnt vmcnt(0)
	v_cmp_eq_u32_e32 vcc, v0, v2
	s_and_saveexec_b64 s[10:11], vcc
	s_cbranch_execz .LBB0_1489
	s_mov_b32 s2, 1
	s_mov_b64 s[40:41], 0
	s_branch .LBB0_1480

.LBB0_1773:
	s_or_b64 exec, exec, s[10:11]
	v_cvt_f32_u32_e32 v5, v3
	s_waitcnt vmcnt(0)
	v_readfirstlane_b32 s1, v4
	v_sub_u32_e32 v4, 0, v3
	v_rcp_iflag_f32_e32 v5, v5
	v_add_u32_e32 v6, s1, v2
	v_mul_f32_e32 v5, 0x4f7ffffe, v5
	v_cvt_u32_f32_e32 v5, v5
	v_mul_lo_u32 v2, v4, v5
	v_mul_hi_u32 v2, v5, v2
	v_add_u32_e32 v2, v5, v2
	v_mul_hi_u32 v2, v6, v2
	v_mul_lo_u32 v4, v2, v3
	v_sub_u32_e32 v4, v6, v4
	v_add_u32_e32 v5, 1, v2
	v_cmp_ge_u32_e32 vcc, v4, v3
	s_nop 1
	v_cndmask_b32_e32 v2, v2, v5, vcc
	v_sub_u32_e32 v5, v4, v3
	v_cndmask_b32_e32 v4, v4, v5, vcc
	v_add_u32_e32 v5, 1, v2
	v_cmp_ge_u32_e32 vcc, v4, v3
	v_add_u32_e32 v4, 1, v6
	s_nop 0
	v_cndmask_b32_e32 v2, v2, v5, vcc
	v_mul_lo_u32 v5, v3, v2
	v_add_u32_e32 v3, v5, v3
	v_cmp_ne_u32_e32 vcc, v4, v3
	s_and_saveexec_b64 s[2:3], vcc
	s_xor_b64 s[8:9], exec, s[2:3]
	s_cbranch_execz .LBB0_1787
	s_movk_i32 s14, 0xd40
	s_lshl_b64 s[2:3], s[14:15], 2
	s_add_u32 s12, s4, s2
	s_addc_u32 s13, s5, s3
	s_waitcnt lgkmcnt(0)
	global_load_dword v0, v1, s[12:13] sc1
	s_waitcnt vmcnt(0)
	v_cmp_eq_u32_e32 vcc, v0, v2
	s_and_saveexec_b64 s[10:11], vcc
	s_cbranch_execz .LBB0_1786
	s_mov_b32 s1, 1
	s_mov_b64 s[40:41], 0
	s_branch .LBB0_1777
